# phase-0 modulation staging: 18 silu(c) loads issued together with one wait instead of load+wait per iteration (on top of v40)
# baseline (speedup 1.0000x reference)
; __device__ __forceinline__ float siluf_(float x) { return x * sigmoidf_(x); }
; __device__ __forceinline__ void phase_prep(CP pp, LAS unsigned char* lds) {
;     ...
;         for (int idx = tid; idx < 9 * 1024; idx += NTHR) { const int r = idx >> 10, k = idx & 1023; const float v = r < 8 ? c[r * 1024 + k] : cctx[k]; S[idx] = siluf_(v); }
.LBB0_452:
	s_waitcnt vmcnt(0)
	v_mov_b32_e32 v12, v163
	s_mov_b32 s2, s36
	s_cmpk_gt_i32 s2, 0x8f
	v_and_b32_e32 v80, 63, v12
	v_ashrrev_i32_e32 v81, 6, v12
	s_cbranch_scc1 .LBB0_466
	s_load_dwordx4 s[8:11], s[52:53], 0x18
	s_load_dwordx2 s[12:13], s[52:53], 0x28
	s_movk_i32 s2, 0x2400
	v_cmp_gt_i32_e32 vcc, s2, v12
	s_and_saveexec_b64 s[14:15], vcc
	s_cbranch_execz .LBB0_456
	s_load_dwordx2 s[4:5], s[52:53], 0x8
	v_ashrrev_i32_e32 v13, 31, v12
	s_waitcnt lgkmcnt(0)
	v_lshl_add_u32 v2, v12, 2, 0
	s_mov_b64 s[20:21], 0
	v_mov_b32_e32 v3, v12
	v_lshl_add_u64 v[0:1], v[12:13], 2, s[4:5]
	v_mov_b32_e32 v7, v2
	global_load_dword v20, v7, s[4:5]
	global_load_dword v21, v7, s[4:5] offset:2048
	v_add_u32_e32 v7, 0x1000, v7
	global_load_dword v22, v7, s[4:5]
	global_load_dword v23, v7, s[4:5] offset:2048
	v_add_u32_e32 v7, 0x1000, v7
	global_load_dword v24, v7, s[4:5]
	global_load_dword v25, v7, s[4:5] offset:2048
	v_add_u32_e32 v7, 0x1000, v7
	global_load_dword v26, v7, s[4:5]
	global_load_dword v27, v7, s[4:5] offset:2048
	v_add_u32_e32 v7, 0x1000, v7
	global_load_dword v28, v7, s[4:5]
	global_load_dword v29, v7, s[4:5] offset:2048
	v_add_u32_e32 v7, 0x1000, v7
	global_load_dword v30, v7, s[4:5]
	global_load_dword v31, v7, s[4:5] offset:2048
	v_add_u32_e32 v7, 0x1000, v7
	global_load_dword v32, v7, s[4:5]
	global_load_dword v33, v7, s[4:5] offset:2048
	v_add_u32_e32 v7, 0x1000, v7
	global_load_dword v34, v7, s[4:5]
	global_load_dword v35, v7, s[4:5] offset:2048
	global_load_dword v36, v2, s[8:9]
	global_load_dword v37, v2, s[8:9] offset:2048
	s_waitcnt vmcnt(9)
	v_mul_f32_e32 v38, 0xbfb8aa3b, v20
	v_mul_f32_e32 v39, 0xbfb8aa3b, v21
	v_mul_f32_e32 v40, 0xbfb8aa3b, v22
	v_mul_f32_e32 v41, 0xbfb8aa3b, v23
	v_mul_f32_e32 v42, 0xbfb8aa3b, v24
	v_mul_f32_e32 v43, 0xbfb8aa3b, v25
	v_mul_f32_e32 v44, 0xbfb8aa3b, v26
	v_mul_f32_e32 v45, 0xbfb8aa3b, v27
	v_mul_f32_e32 v46, 0xbfb8aa3b, v28
	v_exp_f32_e32 v38, v38
	v_exp_f32_e32 v39, v39
	v_exp_f32_e32 v40, v40
	v_exp_f32_e32 v41, v41
	v_exp_f32_e32 v42, v42
	v_exp_f32_e32 v43, v43
	v_exp_f32_e32 v44, v44
	v_exp_f32_e32 v45, v45
	v_exp_f32_e32 v46, v46
	v_add_f32_e32 v38, 1.0, v38
	v_add_f32_e32 v39, 1.0, v39
	v_add_f32_e32 v40, 1.0, v40
	v_add_f32_e32 v41, 1.0, v41
	v_add_f32_e32 v42, 1.0, v42
	v_add_f32_e32 v43, 1.0, v43
	v_add_f32_e32 v44, 1.0, v44
	v_add_f32_e32 v45, 1.0, v45
	v_add_f32_e32 v46, 1.0, v46
	v_rcp_f32_e32 v38, v38
	v_rcp_f32_e32 v39, v39
	v_rcp_f32_e32 v40, v40
	v_rcp_f32_e32 v41, v41
	v_rcp_f32_e32 v42, v42
	v_rcp_f32_e32 v43, v43
	v_rcp_f32_e32 v44, v44
	v_rcp_f32_e32 v45, v45
	v_rcp_f32_e32 v46, v46
	v_mul_f32_e32 v20, v20, v38
	v_mul_f32_e32 v21, v21, v39
	v_mul_f32_e32 v22, v22, v40
	v_mul_f32_e32 v23, v23, v41
	v_mul_f32_e32 v24, v24, v42
	v_mul_f32_e32 v25, v25, v43
	v_mul_f32_e32 v26, v26, v44
	v_mul_f32_e32 v27, v27, v45
	v_mul_f32_e32 v28, v28, v46
	ds_write_b32 v2, v20 offset:0
	ds_write_b32 v2, v21 offset:2048
	ds_write_b32 v2, v22 offset:4096
	ds_write_b32 v2, v23 offset:6144
	ds_write_b32 v2, v24 offset:8192
	ds_write_b32 v2, v25 offset:10240
	ds_write_b32 v2, v26 offset:12288
	ds_write_b32 v2, v27 offset:14336
	ds_write_b32 v2, v28 offset:16384
	s_waitcnt vmcnt(0)
	v_mul_f32_e32 v47, 0xbfb8aa3b, v29
	v_mul_f32_e32 v48, 0xbfb8aa3b, v30
	v_mul_f32_e32 v49, 0xbfb8aa3b, v31
	v_mul_f32_e32 v50, 0xbfb8aa3b, v32
	v_mul_f32_e32 v51, 0xbfb8aa3b, v33
	v_mul_f32_e32 v52, 0xbfb8aa3b, v34
	v_mul_f32_e32 v53, 0xbfb8aa3b, v35
	v_mul_f32_e32 v54, 0xbfb8aa3b, v36
	v_mul_f32_e32 v55, 0xbfb8aa3b, v37
	v_exp_f32_e32 v47, v47
	v_exp_f32_e32 v48, v48
	v_exp_f32_e32 v49, v49
	v_exp_f32_e32 v50, v50
	v_exp_f32_e32 v51, v51
	v_exp_f32_e32 v52, v52
	v_exp_f32_e32 v53, v53
	v_exp_f32_e32 v54, v54
	v_exp_f32_e32 v55, v55
	v_add_f32_e32 v47, 1.0, v47
	v_add_f32_e32 v48, 1.0, v48
	v_add_f32_e32 v49, 1.0, v49
	v_add_f32_e32 v50, 1.0, v50
	v_add_f32_e32 v51, 1.0, v51
	v_add_f32_e32 v52, 1.0, v52
	v_add_f32_e32 v53, 1.0, v53
	v_add_f32_e32 v54, 1.0, v54
	v_add_f32_e32 v55, 1.0, v55
	v_rcp_f32_e32 v47, v47
	v_rcp_f32_e32 v48, v48
	v_rcp_f32_e32 v49, v49
	v_rcp_f32_e32 v50, v50
	v_rcp_f32_e32 v51, v51
	v_rcp_f32_e32 v52, v52
	v_rcp_f32_e32 v53, v53
	v_rcp_f32_e32 v54, v54
	v_rcp_f32_e32 v55, v55
	v_mul_f32_e32 v29, v29, v47
	v_mul_f32_e32 v30, v30, v48
	v_mul_f32_e32 v31, v31, v49
	v_mul_f32_e32 v32, v32, v50
	v_mul_f32_e32 v33, v33, v51
	v_mul_f32_e32 v34, v34, v52
	v_mul_f32_e32 v35, v35, v53
	v_mul_f32_e32 v36, v36, v54
	v_mul_f32_e32 v37, v37, v55
	ds_write_b32 v2, v29 offset:18432
	ds_write_b32 v2, v30 offset:20480
	ds_write_b32 v2, v31 offset:22528
	ds_write_b32 v2, v32 offset:24576
	ds_write_b32 v2, v33 offset:26624
	ds_write_b32 v2, v34 offset:28672
	ds_write_b32 v2, v35 offset:30720
	ds_write_b32 v2, v36 offset:32768
	ds_write_b32 v2, v37 offset:34816
